# norm1/norm2 normalized-activation stores marked sc1 (write-through), so the phase-end L2 write-back has less to flush
# speedup vs baseline: 1.0374x; 1.0020x over previous
.LBB0_260:
	s_or_b64 exec, exec, s[6:7]
	v_pk_mul_f32 v[66:67], v[12:13], v[12:13]
	v_pk_mul_f32 v[68:69], v[8:9], v[8:9]
	v_pk_mul_f32 v[62:63], v[14:15], v[14:15]
	v_pk_mul_f32 v[64:65], v[10:11], v[10:11]
	v_mov_b32_e32 v70, v66
	v_mov_b32_e32 v71, v68
	v_mov_b32_e32 v68, v67
	v_pk_add_f32 v[66:67], v[70:71], v[68:69]
	v_mov_b32_e32 v68, v62
	v_mov_b32_e32 v69, v64
	v_pk_mul_f32 v[58:59], v[0:1], v[0:1]
	v_pk_mul_f32 v[60:61], v[4:5], v[4:5]
	v_pk_add_f32 v[66:67], v[68:69], v[66:67]
	v_mov_b32_e32 v64, v63
	v_pk_mul_f32 v[54:55], v[2:3], v[2:3]
	v_pk_mul_f32 v[56:57], v[6:7], v[6:7]
	v_pk_add_f32 v[62:63], v[64:65], v[66:67]
	v_mov_b32_e32 v64, v58
	v_mov_b32_e32 v65, v60
	v_mov_b32_e32 v60, v59
	v_pk_add_f32 v[58:59], v[64:65], v[60:61]
	v_mov_b32_e32 v60, v54
	v_mov_b32_e32 v61, v56
	v_pk_add_f32 v[58:59], v[60:61], v[58:59]
	v_mov_b32_e32 v56, v55
	v_pk_add_f32 v[54:55], v[56:57], v[58:59]
	v_add_f32_e32 v39, v62, v63
	v_add_f32_e32 v39, v55, v39
	v_add_f32_e32 v39, v54, v39
	ds_bpermute_b32 v41, v47, v39
	s_and_b64 s[0:1], exec, vcc
	s_or_b64 s[40:41], s[0:1], s[40:41]
	s_mov_b32 s0, 0x800000
	v_mov_b64_e32 v[54:55], s[66:67]
	s_waitcnt lgkmcnt(0)
	v_add_f32_e32 v39, v39, v41
	ds_bpermute_b32 v41, v48, v39
	v_mov_b32_e32 v43, v129
	v_lshl_add_u64 v[34:35], v[34:35], 0, s[30:31]
	s_waitcnt lgkmcnt(0)
	v_add_f32_e32 v39, v39, v41
	ds_bpermute_b32 v41, v49, v39
	s_waitcnt lgkmcnt(0)
	v_add_f32_e32 v39, v39, v41
	ds_bpermute_b32 v41, v50, v39
	s_waitcnt lgkmcnt(0)
	v_add_f32_e32 v39, v39, v41
	ds_bpermute_b32 v41, v51, v39
	s_waitcnt lgkmcnt(0)
	v_add_f32_e32 v39, v39, v41
	ds_bpermute_b32 v41, v52, v39
	s_waitcnt lgkmcnt(0)
	v_add_f32_e32 v39, v39, v41
	v_fmamk_f32 v39, v39, 0x3a800000, v225
	v_cmp_gt_f32_e32 vcc, s0, v39
	v_mul_f32_e32 v41, 0x4b800000, v39
	s_movk_i32 s0, 0x1fff
	v_cndmask_b32_e32 v39, v39, v41, vcc
	v_rsq_f32_e32 v39, v39
	s_nop 0
	v_mul_f32_e32 v41, 0x45800000, v39
	v_cndmask_b32_e32 v46, v39, v41, vcc
	v_add_u32_e32 v39, 0xffffe000, v44
	v_lshrrev_b32_e32 v39, 10, v39
	v_add_u32_e32 v39, 1, v39
	v_cmp_lt_i32_e32 vcc, s0, v44
	v_readlane_b32 s0, v254, 62
	v_mov_b32_e32 v41, v129
	v_cndmask_b32_e32 v39, 0, v39, vcc
	v_add_u32_e32 v39, s0, v39
	s_movk_i32 s0, 0x6000
	v_mad_u64_u32 v[54:55], s[0:1], v39, s0, v[54:55]
	s_mov_b64 s[0:1], 0x3000
	s_nop 0
	v_lshl_add_u64 v[94:95], v[54:55], 0, s[0:1]
	s_mov_b64 s[0:1], 0x4000
	v_lshl_add_u64 v[98:99], v[54:55], 0, s[0:1]
	global_load_dwordx4 v[54:57], v[32:33], off
	v_lshl_add_u64 v[58:59], v[94:95], 0, v[128:129]
	v_lshl_add_u64 v[62:63], v[98:99], 0, v[128:129]
	global_load_dwordx4 v[58:61], v[58:59], off
	s_nop 0
	global_load_dwordx4 v[62:65], v[62:63], off
	s_nop 0
	global_load_dwordx4 v[66:69], v[32:33], off offset:1024
	v_mov_b32_e32 v39, v129
	v_lshl_add_u64 v[70:71], v[94:95], 0, v[38:39]
	v_lshl_add_u64 v[74:75], v[98:99], 0, v[38:39]
	global_load_dwordx4 v[70:73], v[70:71], off
	s_nop 0
	global_load_dwordx4 v[74:77], v[74:75], off
	s_nop 0
	global_load_dwordx4 v[78:81], v[32:33], off offset:2048
	v_lshl_add_u64 v[82:83], v[94:95], 0, v[40:41]
	v_lshl_add_u64 v[86:87], v[98:99], 0, v[40:41]
	global_load_dwordx4 v[82:85], v[82:83], off
	s_nop 0
	global_load_dwordx4 v[86:89], v[86:87], off
	s_nop 0
	global_load_dwordx4 v[90:93], v[32:33], off offset:3072
	v_lshl_add_u64 v[94:95], v[94:95], 0, v[42:43]
	v_lshl_add_u64 v[98:99], v[98:99], 0, v[42:43]
	global_load_dwordx4 v[94:97], v[94:95], off
	v_pk_mul_f32 v[14:15], v[14:15], v[46:47] op_sel_hi:[1,0]
	global_load_dwordx4 v[98:101], v[98:99], off
	v_pk_mul_f32 v[12:13], v[12:13], v[46:47] op_sel_hi:[1,0]
	v_pk_mul_f32 v[10:11], v[10:11], v[46:47] op_sel_hi:[1,0]
	v_pk_mul_f32 v[8:9], v[8:9], v[46:47] op_sel_hi:[1,0]
	v_pk_mul_f32 v[6:7], v[6:7], v[46:47] op_sel_hi:[1,0]
	v_pk_mul_f32 v[4:5], v[4:5], v[46:47] op_sel_hi:[1,0]
	v_pk_mul_f32 v[2:3], v[2:3], v[46:47] op_sel_hi:[1,0]
	v_pk_mul_f32 v[0:1], v[0:1], v[46:47] op_sel_hi:[1,0]
	v_mov_b32_e32 v44, v45
	s_waitcnt vmcnt(11)
	v_pk_mul_f32 v[12:13], v[54:55], v[12:13]
	v_pk_mul_f32 v[14:15], v[56:57], v[14:15]
	s_waitcnt vmcnt(9)
	v_pk_add_f32 v[54:55], v[64:65], 1.0 op_sel_hi:[1,0]
	v_pk_add_f32 v[56:57], v[62:63], 1.0 op_sel_hi:[1,0]
	v_pk_fma_f32 v[14:15], v[54:55], v[14:15], v[60:61]
	v_pk_fma_f32 v[12:13], v[56:57], v[12:13], v[58:59]
	s_waitcnt vmcnt(8)
	v_pk_mul_f32 v[8:9], v[66:67], v[8:9]
	v_cvt_pk_bf16_f32 v12, v12, v13
	v_cvt_pk_bf16_f32 v13, v14, v15
	global_store_dwordx2 v[36:37], v[12:13], off offset:-1024 sc1
	v_pk_mul_f32 v[10:11], v[68:69], v[10:11]
	s_waitcnt vmcnt(7)
	v_pk_add_f32 v[12:13], v[76:77], 1.0 op_sel_hi:[1,0]
	v_pk_add_f32 v[14:15], v[74:75], 1.0 op_sel_hi:[1,0]
	v_pk_fma_f32 v[10:11], v[12:13], v[10:11], v[72:73]
	v_pk_fma_f32 v[8:9], v[14:15], v[8:9], v[70:71]
	s_waitcnt vmcnt(6)
	v_pk_mul_f32 v[4:5], v[78:79], v[4:5]
	v_cvt_pk_bf16_f32 v8, v8, v9
	v_cvt_pk_bf16_f32 v9, v10, v11
	global_store_dwordx2 v[36:37], v[8:9], off offset:-512 sc1
	v_pk_mul_f32 v[6:7], v[80:81], v[6:7]
	s_waitcnt vmcnt(5)
	v_pk_add_f32 v[8:9], v[88:89], 1.0 op_sel_hi:[1,0]
	v_pk_add_f32 v[10:11], v[86:87], 1.0 op_sel_hi:[1,0]
	v_pk_fma_f32 v[6:7], v[8:9], v[6:7], v[84:85]
	v_pk_fma_f32 v[4:5], v[10:11], v[4:5], v[82:83]
	s_waitcnt vmcnt(4)
	v_pk_mul_f32 v[0:1], v[90:91], v[0:1]
	v_cvt_pk_bf16_f32 v4, v4, v5
	v_cvt_pk_bf16_f32 v5, v6, v7
	global_store_dwordx2 v[36:37], v[4:5], off sc1
	v_pk_mul_f32 v[2:3], v[92:93], v[2:3]
	s_waitcnt vmcnt(3)
	v_pk_add_f32 v[4:5], v[100:101], 1.0 op_sel_hi:[1,0]
	v_pk_add_f32 v[6:7], v[98:99], 1.0 op_sel_hi:[1,0]
	v_pk_fma_f32 v[2:3], v[2:3], v[4:5], v[96:97]
	v_pk_fma_f32 v[0:1], v[0:1], v[6:7], v[94:95]
	v_mov_b32_e32 v12, v16
	v_cvt_pk_bf16_f32 v0, v0, v1
	v_cvt_pk_bf16_f32 v1, v2, v3
	global_store_dwordx2 v[36:37], v[0:1], off offset:512 sc1
	v_lshl_add_u64 v[36:37], v[36:37], 0, s[38:39]
	v_mov_b32_e32 v13, v17
	v_mov_b32_e32 v14, v18
	v_mov_b32_e32 v15, v19
	v_mov_b32_e32 v8, v20
	v_mov_b32_e32 v9, v21
	v_mov_b32_e32 v10, v22
	v_mov_b32_e32 v11, v23
	v_mov_b32_e32 v4, v24
	v_mov_b32_e32 v5, v25
	v_mov_b32_e32 v6, v26
	v_mov_b32_e32 v7, v27
	v_mov_b32_e32 v0, v28
	v_mov_b32_e32 v1, v29
	v_mov_b32_e32 v2, v30
	v_mov_b32_e32 v3, v31
	s_andn2_b64 exec, exec, s[40:41]
	s_cbranch_execz .LBB0_263

.LBB0_1665:
	s_or_b64 exec, exec, s[6:7]
	v_add_u32_e32 v37, 0xffffe000, v36
	v_lshrrev_b32_e32 v37, 10, v37
	s_movk_i32 s6, 0x1fff
	v_add_u32_e32 v37, 1, v37
	v_cmp_lt_i32_e32 vcc, s6, v36
	v_readlane_b32 s6, v254, 62
	v_pk_mul_f32 v[56:57], v[12:13], v[12:13]
	v_cndmask_b32_e32 v36, 0, v37, vcc
	v_add_u32_e32 v43, s6, v36
	v_mov_b64_e32 v[36:37], s[66:67]
	s_movk_i32 s6, 0x6000
	v_mad_u64_u32 v[36:37], s[6:7], v43, s6, v[36:37]
	v_pk_mul_f32 v[58:59], v[8:9], v[8:9]
	s_mov_b64 s[6:7], 0x1000
	v_pk_mul_f32 v[68:69], v[14:15], v[14:15]
	v_pk_mul_f32 v[70:71], v[10:11], v[10:11]
	v_mov_b32_e32 v60, v56
	v_mov_b32_e32 v61, v58
	v_mov_b32_e32 v58, v57
	v_lshl_add_u64 v[96:97], v[36:37], 0, s[6:7]
	v_lshlrev_b32_e32 v128, 2, v32
	v_pk_add_f32 v[56:57], v[60:61], v[58:59]
	v_mov_b32_e32 v58, v68
	v_mov_b32_e32 v59, v70
	v_lshl_add_u64 v[60:61], v[96:97], 0, v[128:129]
	v_pk_add_f32 v[72:73], v[58:59], v[56:57]
	global_load_dwordx4 v[56:59], v[34:35], off
	v_lshl_add_u64 v[36:37], v[36:37], 0, v[128:129]
	global_load_dwordx4 v[60:63], v[60:61], off
	v_mov_b32_e32 v70, v69
	global_load_dwordx4 v[64:67], v[36:37], off
	global_load_dwordx4 v[76:79], v[36:37], off offset:1024
	v_mov_b32_e32 v43, v129
	v_pk_add_f32 v[94:95], v[70:71], v[72:73]
	v_lshl_add_u64 v[72:73], v[96:97], 0, v[42:43]
	v_pk_mul_f32 v[80:81], v[0:1], v[0:1]
	v_pk_mul_f32 v[82:83], v[4:5], v[4:5]
	global_load_dwordx4 v[68:71], v[34:35], off offset:1024
	v_pk_mul_f32 v[88:89], v[2:3], v[2:3]
	global_load_dwordx4 v[72:75], v[72:73], off
	v_pk_mul_f32 v[92:93], v[6:7], v[6:7]
	v_mov_b32_e32 v84, v80
	v_mov_b32_e32 v85, v82
	v_mov_b32_e32 v82, v81
	v_mov_b32_e32 v45, v129
	v_pk_add_f32 v[80:81], v[84:85], v[82:83]
	v_mov_b32_e32 v82, v88
	v_mov_b32_e32 v83, v92
	v_lshl_add_u64 v[84:85], v[96:97], 0, v[44:45]
	v_pk_add_f32 v[98:99], v[82:83], v[80:81]
	global_load_dwordx4 v[80:83], v[34:35], off offset:2048
	v_mov_b32_e32 v92, v89
	global_load_dwordx4 v[84:87], v[84:85], off
	v_pk_add_f32 v[92:93], v[92:93], v[98:99]
	global_load_dwordx4 v[88:91], v[36:37], off offset:2048
	global_load_dwordx4 v[100:103], v[36:37], off offset:3072
	v_add_f32_e32 v43, v94, v95
	v_mov_b32_e32 v47, v129
	v_add_f32_e32 v43, v93, v43
	v_lshl_add_u64 v[96:97], v[96:97], 0, v[46:47]
	v_add_f32_e32 v43, v92, v43
	global_load_dwordx4 v[92:95], v[34:35], off offset:3072
	ds_bpermute_b32 v45, v33, v43
	global_load_dwordx4 v[96:99], v[96:97], off
	s_mov_b32 s6, 0x800000
	v_lshl_add_u64 v[38:39], v[38:39], 0, s[4:5]
	s_waitcnt lgkmcnt(0)
	v_add_f32_e32 v43, v43, v45
	ds_bpermute_b32 v36, v50, v43
	s_waitcnt lgkmcnt(0)
	v_add_f32_e32 v36, v43, v36
	ds_bpermute_b32 v37, v51, v36
	s_waitcnt lgkmcnt(0)
	v_add_f32_e32 v36, v36, v37
	ds_bpermute_b32 v37, v52, v36
	s_waitcnt lgkmcnt(0)
	v_add_f32_e32 v36, v36, v37
	ds_bpermute_b32 v37, v53, v36
	s_waitcnt lgkmcnt(0)
	v_add_f32_e32 v36, v36, v37
	ds_bpermute_b32 v37, v54, v36
	s_waitcnt lgkmcnt(0)
	v_add_f32_e32 v36, v36, v37
	v_fmamk_f32 v36, v36, 0x3a800000, v225
	v_mul_f32_e32 v37, 0x4b800000, v36
	v_cmp_gt_f32_e32 vcc, s6, v36
	s_nop 1
	v_cndmask_b32_e32 v36, v36, v37, vcc
	v_rsq_f32_e32 v36, v36
	s_nop 0
	v_mul_f32_e32 v37, 0x45800000, v36
	v_cndmask_b32_e32 v36, v36, v37, vcc
	v_pk_mul_f32 v[14:15], v[14:15], v[36:37] op_sel_hi:[1,0]
	v_pk_mul_f32 v[12:13], v[12:13], v[36:37] op_sel_hi:[1,0]
	s_waitcnt vmcnt(11)
	v_pk_mul_f32 v[14:15], v[58:59], v[14:15]
	v_pk_mul_f32 v[12:13], v[56:57], v[12:13]
	s_waitcnt vmcnt(10)
	v_pk_add_f32 v[56:57], v[62:63], 1.0 op_sel_hi:[1,0]
	v_pk_add_f32 v[58:59], v[60:61], 1.0 op_sel_hi:[1,0]
	s_waitcnt vmcnt(9)
	v_pk_fma_f32 v[14:15], v[56:57], v[14:15], v[66:67]
	v_pk_fma_f32 v[12:13], v[58:59], v[12:13], v[64:65]
	v_pk_mul_f32 v[10:11], v[10:11], v[36:37] op_sel_hi:[1,0]
	v_pk_mul_f32 v[8:9], v[8:9], v[36:37] op_sel_hi:[1,0]
	v_cvt_pk_bf16_f32 v12, v12, v13
	v_cvt_pk_bf16_f32 v13, v14, v15
	global_store_dwordx2 v[40:41], v[12:13], off offset:-1024 sc1
	s_waitcnt vmcnt(8)
	v_pk_mul_f32 v[8:9], v[68:69], v[8:9]
	v_pk_mul_f32 v[10:11], v[70:71], v[10:11]
	s_waitcnt vmcnt(7)
	v_pk_add_f32 v[12:13], v[74:75], 1.0 op_sel_hi:[1,0]
	v_pk_add_f32 v[14:15], v[72:73], 1.0 op_sel_hi:[1,0]
	v_pk_fma_f32 v[10:11], v[12:13], v[10:11], v[78:79]
	v_pk_fma_f32 v[8:9], v[14:15], v[8:9], v[76:77]
	v_pk_mul_f32 v[6:7], v[6:7], v[36:37] op_sel_hi:[1,0]
	v_cvt_pk_bf16_f32 v8, v8, v9
	v_cvt_pk_bf16_f32 v9, v10, v11
	v_pk_mul_f32 v[4:5], v[4:5], v[36:37] op_sel_hi:[1,0]
	global_store_dwordx2 v[40:41], v[8:9], off offset:-512 sc1
	s_waitcnt vmcnt(7)
	v_pk_mul_f32 v[4:5], v[80:81], v[4:5]
	v_pk_mul_f32 v[6:7], v[82:83], v[6:7]
	s_waitcnt vmcnt(6)
	v_pk_add_f32 v[8:9], v[86:87], 1.0 op_sel_hi:[1,0]
	v_pk_add_f32 v[10:11], v[84:85], 1.0 op_sel_hi:[1,0]
	s_waitcnt vmcnt(5)
	v_pk_fma_f32 v[6:7], v[8:9], v[6:7], v[90:91]
	v_pk_fma_f32 v[4:5], v[10:11], v[4:5], v[88:89]
	v_pk_mul_f32 v[2:3], v[2:3], v[36:37] op_sel_hi:[1,0]
	v_cvt_pk_bf16_f32 v4, v4, v5
	v_cvt_pk_bf16_f32 v5, v6, v7
	v_pk_mul_f32 v[0:1], v[0:1], v[36:37] op_sel_hi:[1,0]
	global_store_dwordx2 v[40:41], v[4:5], off sc1
	s_waitcnt vmcnt(4)
	v_pk_mul_f32 v[0:1], v[92:93], v[0:1]
	v_pk_mul_f32 v[2:3], v[94:95], v[2:3]
	s_waitcnt vmcnt(3)
	v_pk_add_f32 v[4:5], v[98:99], 1.0 op_sel_hi:[1,0]
	v_pk_add_f32 v[6:7], v[96:97], 1.0 op_sel_hi:[1,0]
	v_pk_fma_f32 v[2:3], v[2:3], v[4:5], v[102:103]
	v_pk_fma_f32 v[0:1], v[0:1], v[6:7], v[100:101]
	v_cmp_lt_i32_e32 vcc, s92, v48
	v_cvt_pk_bf16_f32 v0, v0, v1
	v_cvt_pk_bf16_f32 v1, v2, v3
	global_store_dwordx2 v[40:41], v[0:1], off offset:512 sc1
	v_lshl_add_u64 v[40:41], v[40:41], 0, s[30:31]
	s_or_b64 s[36:37], vcc, s[36:37]
	v_mov_b32_e32 v36, v48
	v_mov_b32_e32 v12, v28
	v_mov_b32_e32 v13, v29
	v_mov_b32_e32 v14, v30
	v_mov_b32_e32 v15, v31
	v_mov_b32_e32 v8, v24
	v_mov_b32_e32 v9, v25
	v_mov_b32_e32 v10, v26
	v_mov_b32_e32 v11, v27
	v_mov_b32_e32 v4, v20
	v_mov_b32_e32 v5, v21
	v_mov_b32_e32 v6, v22
	v_mov_b32_e32 v7, v23
	v_mov_b32_e32 v0, v16
	v_mov_b32_e32 v1, v17
	v_mov_b32_e32 v2, v18
	v_mov_b32_e32 v3, v19
	s_andn2_b64 exec, exec, s[36:37]
	s_cbranch_execz .LBB0_1677
